# ln_mod loop: next row's x/pos loads issued mid-iteration (software pipelined) with counted waits
# baseline (speedup 1.0000x reference)
.LBB0_376:
	s_andn2_b64 vcc, exec, s[42:43]
	s_mov_b64 s[0:1], 0
	s_cbranch_vccnz .LBB0_517
	s_cmp_gt_i32 s10, 0
	s_mov_b64 s[22:23], -1
	s_cbranch_scc0 .LBB0_515
	v_mov_b32_e32 v0, v228
	v_readlane_b32 s0, v251, 20
	v_ashrrev_i32_e32 v3, 6, v0
	s_nop 0
	v_add_u32_e32 v2, s0, v3
	s_mov_b32 s0, 0x8800
	v_cmp_gt_i32_e32 vcc, s0, v2
	s_and_saveexec_b64 s[0:1], vcc
	s_cbranch_execz .LBB0_385
	v_lshlrev_b32_e32 v0, 2, v0
	v_and_b32_e32 v4, 64, v238
	v_and_b32_e32 v10, 0xfc, v0
	v_xor_b32_e32 v0, 16, v238
	v_add_u32_e32 v4, 64, v4
	v_cmp_lt_i32_e32 vcc, v0, v4
	v_readlane_b32 s22, v251, 15
	v_readlane_b32 s23, v251, 16
	v_cndmask_b32_e32 v0, v238, v0, vcc
	v_lshlrev_b32_e32 v21, 2, v0
	v_xor_b32_e32 v0, 32, v238
	v_cmp_lt_i32_e32 vcc, v0, v4
	v_readlane_b32 s2, v254, 10
	s_nop 0
	v_cndmask_b32_e32 v0, v238, v0, vcc
	v_lshlrev_b32_e32 v26, 2, v0
	v_lshlrev_b32_e32 v0, 2, v10
	v_lshl_add_u64 v[4:5], s[22:23], 0, v[0:1]
	v_lshl_add_u64 v[6:7], s[8:9], 0, v[0:1]
	v_lshlrev_b32_e32 v0, 1, v10
	v_lshl_add_u32 v27, v3, 3, s2
	v_readlane_b32 s2, v254, 6
	v_lshl_add_u64 v[8:9], s[96:97], 0, v[0:1]
	s_mov_b64 s[22:23], 0
	v_lshl_add_u32 v28, v3, 9, s2
	v_lshlrev_b32_e32 v0, 2, v10
	s_mov_b32 s24, 0
	s_branch .LBB0_381
.LBB0_380:
	s_or_b64 exec, exec, s[26:27]
	s_cmp_eq_u32 s24, 1
	s_cbranch_scc1 .Lln_have
	v_and_b32_e32 v13, 0x7e00, v27
	v_and_b32_e32 v12, 0x7e00, v28
	v_lshl_add_u64 v[38:39], v[10:11], 0, v[0:1]
	v_lshlrev_b32_e32 v10, 2, v13
	v_mov_b32_e32 v11, v1
	v_lshl_add_u64 v[40:41], v[4:5], 0, v[10:11]
	v_lshlrev_b32_e32 v10, 2, v12
	v_lshl_add_u64 v[10:11], v[6:7], 0, v[10:11]
	s_mov_b32 s2, 0x1620000
	v_add_co_u32_e32 v42, vcc, s2, v10
	v_addc_co_u32_e32 v43, vcc, 0, v11, vcc
	global_load_dwordx4 v[30:33], v[38:39], off
	global_load_dwordx4 v[34:37], v[40:41], off
	global_load_dwordx4 v[82:85], v[38:39], off offset:1024
	global_load_dwordx4 v[86:89], v[40:41], off offset:1024
	global_load_dwordx4 v[90:93], v[38:39], off offset:2048
	global_load_dwordx4 v[94:97], v[42:43], off
	global_load_dwordx4 v[44:47], v[38:39], off offset:3072
	global_load_dwordx4 v[16:19], v[42:43], off offset:1024
.Lln_have:
	v_min_i32_e32 v10, 0x8000, v2
	v_ashrrev_i32_e32 v10, 12, v10
	v_mul_i32_i24_e32 v10, 0xc00, v10
	v_readlane_b32 s24, v252, 15
	v_ashrrev_i32_e32 v11, 31, v10
	v_readlane_b32 s25, v252, 16
	s_nop 1
	v_lshl_add_u64 v[10:11], v[10:11], 2, s[24:25]
	v_lshl_add_u64 v[98:99], v[10:11], 0, v[0:1]
	v_lshlrev_b64 v[10:11], 11, v[2:3]
	s_mov_b64 s[24:25], 0x1000
	v_lshl_add_u64 v[100:101], v[98:99], 0, s[24:25]
	v_lshl_add_u64 v[10:11], v[8:9], 0, v[10:11]
	global_load_dwordx4 v[104:107], v[100:101], off offset:1024
	global_load_dwordx4 v[108:111], v[100:101], off offset:2048
	global_load_dwordx4 v[112:115], v[100:101], off
	global_load_dwordx4 v[116:119], v[98:99], off
	global_load_dwordx4 v[120:123], v[98:99], off offset:1024
	global_load_dwordx4 v[124:127], v[100:101], off offset:3072
	global_load_dwordx4 v[128:131], v[98:99], off offset:2048
	global_load_dwordx4 v[132:135], v[98:99], off offset:3072
	s_waitcnt vmcnt(14)
	v_pk_fma_f32 v[22:23], v[20:21], v[36:37], v[32:33] op_sel_hi:[0,1,1]
	v_pk_fma_f32 v[24:25], v[20:21], v[34:35], v[30:31] op_sel_hi:[0,1,1]
	v_add_f32_e32 v3, 0, v24
	v_add_f32_e32 v3, v3, v25
	v_add_f32_e32 v3, v3, v22
	v_add_f32_e32 v3, v3, v23
	s_waitcnt vmcnt(12)
	v_pk_fma_f32 v[58:59], v[20:21], v[88:89], v[84:85] op_sel_hi:[0,1,1]
	v_pk_fma_f32 v[60:61], v[20:21], v[86:87], v[82:83] op_sel_hi:[0,1,1]
	v_add_f32_e32 v3, v3, v60
	v_add_f32_e32 v3, v3, v61
	v_add_f32_e32 v3, v3, v58
	v_add_f32_e32 v3, v3, v59
	s_waitcnt vmcnt(10)
	v_pk_fma_f32 v[64:65], v[20:21], v[94:95], v[90:91] op_sel_hi:[0,1,1]
	v_pk_fma_f32 v[62:63], v[20:21], v[96:97], v[92:93] op_sel_hi:[0,1,1]
	v_add_f32_e32 v3, v3, v64
	v_add_f32_e32 v3, v3, v65
	v_add_f32_e32 v3, v3, v62
	v_add_f32_e32 v3, v3, v63
	s_waitcnt vmcnt(8)
	v_pk_fma_f32 v[12:13], v[20:21], v[16:17], v[44:45] op_sel_hi:[0,1,1]
	v_pk_fma_f32 v[14:15], v[20:21], v[18:19], v[46:47] op_sel_hi:[0,1,1]
	v_add_f32_e32 v3, v3, v12
	v_add_f32_e32 v3, v3, v13
	v_add_f32_e32 v3, v3, v14
	v_add_f32_e32 v3, v3, v15
	v_readlane_b32 s24, v251, 19
	v_readlane_b32 s25, v253, 56
	s_nop 1
	v_add_u32_e32 v48, s24, v2
	v_add_u32_e32 v49, s41, v27
	v_add_u32_e32 v50, s25, v28
	s_nop 0
	v_readfirstlane_b32 s25, v48
	s_mov_b32 s24, 0
	s_nop 2
	s_cmp_gt_i32 s25, 0x87ff
	s_cbranch_scc1 .Lln_nopf
	s_cmp_gt_i32 s25, 0x7fff
	s_cselect_b64 s[26:27], s[68:69], s[64:65]
	s_cselect_b32 s2, 0x8000, 0
	s_sub_u32 s2, s25, s2
	s_lshl_b32 s2, s2, 12
	s_add_u32 s26, s26, s2
	s_addc_u32 s27, s27, 0
	v_and_b32_e32 v49, 0x7e00, v49
	v_lshlrev_b32_e32 v38, 2, v49
	v_mov_b32_e32 v39, 0
	v_lshl_add_u64 v[40:41], v[4:5], 0, v[38:39]
	v_and_b32_e32 v50, 0x7e00, v50
	v_lshlrev_b32_e32 v38, 2, v50
	v_lshl_add_u64 v[42:43], v[6:7], 0, v[38:39]
	s_mov_b32 s2, 0x1620000
	v_add_co_u32_e32 v42, vcc, s2, v42
	s_nop 0
	v_addc_co_u32_e32 v43, vcc, 0, v43, vcc
	global_load_dwordx4 v[30:33], v0, s[26:27]
	global_load_dwordx4 v[34:37], v[40:41], off
	global_load_dwordx4 v[82:85], v0, s[26:27] offset:1024
	global_load_dwordx4 v[86:89], v[40:41], off offset:1024
	global_load_dwordx4 v[90:93], v0, s[26:27] offset:2048
	global_load_dwordx4 v[94:97], v[42:43], off
	global_load_dwordx4 v[44:47], v0, s[26:27] offset:3072
	global_load_dwordx4 v[16:19], v[42:43], off offset:1024
	s_mov_b32 s24, 1
.Lln_nopf:
	s_cmp_eq_u32 s24, 0
	s_cbranch_scc1 .Lln_w1a
	s_waitcnt vmcnt(14)
	s_branch .Lln_w1b
.Lln_w1a:
	s_waitcnt vmcnt(6)
.Lln_w1b:
	v_pk_add_f32 v[108:109], v[108:109], 1.0 op_sel_hi:[1,0]
	v_add_f32_dpp v3, v3, v3 quad_perm:[1,0,3,2] row_mask:0xf bank_mask:0xf bound_ctrl:1
	v_pk_add_f32 v[104:105], v[104:105], 1.0 op_sel_hi:[1,0]
	v_pk_add_f32 v[106:107], v[106:107], 1.0 op_sel_hi:[1,0]
	v_add_f32_dpp v3, v3, v3 quad_perm:[2,3,0,1] row_mask:0xf bank_mask:0xf bound_ctrl:1
	v_pk_add_f32 v[110:111], v[110:111], 1.0 op_sel_hi:[1,0]
	s_cmp_eq_u32 s24, 0
	s_cbranch_scc1 .Lln_w2a
	s_waitcnt vmcnt(13)
	s_branch .Lln_w2b

.Lln_w2b:
	v_pk_add_f32 v[112:113], v[112:113], 1.0 op_sel_hi:[1,0]
	v_add_f32_dpp v3, v3, v3 row_half_mirror row_mask:0xf bank_mask:0xf bound_ctrl:1
	v_pk_add_f32 v[114:115], v[114:115], 1.0 op_sel_hi:[1,0]
	s_cmp_eq_u32 s24, 0
	s_cbranch_scc1 .Lln_w3a
	s_waitcnt vmcnt(10)
	s_branch .Lln_w3b

.Lln_w3b:
	v_pk_add_f32 v[124:125], v[124:125], 1.0 op_sel_hi:[1,0]
	v_add_f32_dpp v3, v3, v3 row_mirror row_mask:0xf bank_mask:0xf bound_ctrl:1
	ds_bpermute_b32 v20, v21, v3
	s_waitcnt lgkmcnt(0)
	v_add_f32_e32 v3, v3, v20
	ds_bpermute_b32 v20, v26, v3
	s_waitcnt lgkmcnt(0)
	v_add_f32_e32 v3, v3, v20
	v_mul_f32_e32 v20, 0x3a800000, v3
	v_pk_add_f32 v[24:25], v[24:25], v[20:21] op_sel_hi:[1,0] neg_lo:[0,1] neg_hi:[0,1]
	v_pk_add_f32 v[22:23], v[22:23], v[20:21] op_sel_hi:[1,0] neg_lo:[0,1] neg_hi:[0,1]
	v_pk_mul_f32 v[66:67], v[24:25], v[24:25]
	v_pk_mul_f32 v[68:69], v[22:23], v[22:23]
	v_add_f32_e32 v3, v66, v67
	v_pk_add_f32 v[60:61], v[60:61], v[20:21] op_sel_hi:[1,0] neg_lo:[0,1] neg_hi:[0,1]
	v_add_f32_e32 v3, v68, v3
	v_pk_mul_f32 v[70:71], v[60:61], v[60:61]
	v_add_f32_e32 v3, v69, v3
	v_pk_add_f32 v[58:59], v[58:59], v[20:21] op_sel_hi:[1,0] neg_lo:[0,1] neg_hi:[0,1]
	v_add_f32_e32 v3, v70, v3
	v_pk_mul_f32 v[72:73], v[58:59], v[58:59]
	v_add_f32_e32 v3, v71, v3
	v_pk_add_f32 v[64:65], v[64:65], v[20:21] op_sel_hi:[1,0] neg_lo:[0,1] neg_hi:[0,1]
	v_add_f32_e32 v3, v72, v3
	v_pk_mul_f32 v[74:75], v[64:65], v[64:65]
	v_add_f32_e32 v3, v73, v3
	v_pk_add_f32 v[62:63], v[62:63], v[20:21] op_sel_hi:[1,0] neg_lo:[0,1] neg_hi:[0,1]
	v_add_f32_e32 v3, v74, v3
	v_pk_mul_f32 v[76:77], v[62:63], v[62:63]
	v_add_f32_e32 v3, v75, v3
	v_pk_add_f32 v[12:13], v[12:13], v[20:21] op_sel_hi:[1,0] neg_lo:[0,1] neg_hi:[0,1]
	v_add_f32_e32 v3, v76, v3
	v_pk_mul_f32 v[80:81], v[12:13], v[12:13]
	v_add_f32_e32 v3, v77, v3
	v_pk_add_f32 v[14:15], v[14:15], v[20:21] op_sel_hi:[1,0] neg_lo:[0,1] neg_hi:[0,1]
	v_add_f32_e32 v3, v80, v3
	v_pk_mul_f32 v[78:79], v[14:15], v[14:15]
	v_add_f32_e32 v3, v81, v3
	v_add_f32_e32 v3, v78, v3
	v_add_f32_e32 v3, v79, v3
	s_nop 1
	v_add_f32_dpp v3, v3, v3 quad_perm:[1,0,3,2] row_mask:0xf bank_mask:0xf bound_ctrl:1
	s_nop 1
	v_add_f32_dpp v3, v3, v3 quad_perm:[2,3,0,1] row_mask:0xf bank_mask:0xf bound_ctrl:1
	s_nop 1
	v_add_f32_dpp v3, v3, v3 row_half_mirror row_mask:0xf bank_mask:0xf bound_ctrl:1
	s_nop 1
	v_add_f32_dpp v3, v3, v3 row_mirror row_mask:0xf bank_mask:0xf bound_ctrl:1
	ds_bpermute_b32 v20, v21, v3
	s_waitcnt lgkmcnt(0)
	v_add_f32_e32 v3, v3, v20
	ds_bpermute_b32 v20, v26, v3
	s_waitcnt lgkmcnt(0)
	v_add_f32_e32 v3, v3, v20
	v_fmamk_f32 v3, v3, 0x3a800000, v230
	v_mul_f32_e32 v20, 0x4b800000, v3
	v_cmp_gt_f32_e32 vcc, s72, v3
	s_nop 1
	v_cndmask_b32_e32 v3, v3, v20, vcc
	v_rsq_f32_e32 v3, v3
	s_nop 0
	v_mul_f32_e32 v20, 0x45800000, v3
	v_cndmask_b32_e32 v20, v3, v20, vcc
	v_pk_mul_f32 v[24:25], v[24:25], v[20:21] op_sel_hi:[1,0]
	v_pk_mul_f32 v[22:23], v[22:23], v[20:21] op_sel_hi:[1,0]
	v_pk_fma_f32 v[24:25], v[112:113], v[24:25], v[116:117]
	v_pk_fma_f32 v[22:23], v[114:115], v[22:23], v[118:119]
	v_cvt_pk_bf16_f32 v24, v24, v25
	v_cvt_pk_bf16_f32 v25, v22, v23
	global_store_dwordx2 v[10:11], v[24:25], off
	v_pk_mul_f32 v[22:23], v[60:61], v[20:21] op_sel_hi:[1,0]
	v_pk_mul_f32 v[24:25], v[58:59], v[20:21] op_sel_hi:[1,0]
	v_pk_fma_f32 v[22:23], v[104:105], v[22:23], v[120:121]
	v_pk_fma_f32 v[24:25], v[106:107], v[24:25], v[122:123]
	v_cvt_pk_bf16_f32 v22, v22, v23
	v_cvt_pk_bf16_f32 v23, v24, v25
	v_pk_mul_f32 v[12:13], v[12:13], v[20:21] op_sel_hi:[1,0]
	v_readlane_b32 s2, v251, 19
	global_store_dwordx2 v[10:11], v[22:23], off offset:512
	v_pk_mul_f32 v[22:23], v[64:65], v[20:21] op_sel_hi:[1,0]
	v_pk_mul_f32 v[24:25], v[62:63], v[20:21] op_sel_hi:[1,0]
	s_cmp_eq_u32 s24, 0
	s_cbranch_scc1 .Lln_w4a
	s_waitcnt vmcnt(10)
	s_branch .Lln_w4b

.Lln_w4b:
	v_pk_fma_f32 v[12:13], v[12:13], v[124:125], v[132:133]
	v_pk_mul_f32 v[14:15], v[14:15], v[20:21] op_sel_hi:[1,0]
	v_pk_add_f32 v[132:133], v[126:127], 1.0 op_sel_hi:[1,0]
	v_add_u32_e32 v2, s2, v2
	s_mov_b32 s2, 0x87ff
	v_pk_fma_f32 v[22:23], v[108:109], v[22:23], v[128:129]
	v_pk_fma_f32 v[24:25], v[110:111], v[24:25], v[130:131]
	v_pk_fma_f32 v[14:15], v[14:15], v[132:133], v[134:135]
	v_cmp_lt_i32_e32 vcc, s2, v2
	v_readlane_b32 s2, v253, 56
	v_cvt_pk_bf16_f32 v22, v22, v23
	v_cvt_pk_bf16_f32 v23, v24, v25
	v_cvt_pk_bf16_f32 v12, v12, v13
	v_cvt_pk_bf16_f32 v13, v14, v15
	v_add_u32_e32 v27, s41, v27
	s_or_b64 s[22:23], vcc, s[22:23]
	v_add_u32_e32 v28, s2, v28
	global_store_dwordx2 v[10:11], v[22:23], off offset:1024
	global_store_dwordx2 v[10:11], v[12:13], off offset:1536
	s_andn2_b64 exec, exec, s[22:23]
	s_cbranch_execz .LBB0_385
